# in_proj second-unit A-panel gate: panel counters of all later tiles read with eight loads in flight instead of one serialized round trip per tile
# baseline (speedup 1.0000x reference)
.Lgp_chunkA:
	s_mul_i32 s84, s54, s5
	s_add_i32 s84, s84, s2
	s_cmpk_gt_i32 s84, 0x87f
	s_cbranch_scc1 .LBB0_328
	s_mov_b32 s100, s84
	s_mov_b32 s101, s84
	s_and_b32 s0, s101, 7
	s_lshr_b32 s80, s101, 3
	s_mul_i32 s0, s0, 0x110
	s_add_i32 s0, s0, s80
	s_lshr_b32 s80, s0, 7
	s_lshl_b32 s80, s80, 2
	s_and_b32 s0, s0, 3
	s_or_b32 s0, s80, s0
	s_cmp_lt_i32 s0, 64
	s_cselect_b32 s81, 32, 0x100
	v_mov_b32_e32 v8, s81
	s_lshl_b32 s0, s0, 6
	s_add_u32 s76, s61, s0
	s_addc_u32 s77, s55, 0
	global_load_dword v0, v33, s[76:77] sc1
	s_add_i32 s84, s84, s5
	s_cmpk_gt_i32 s84, 0x87f
	s_cselect_b32 s101, s100, s84
	s_and_b32 s0, s101, 7
	s_lshr_b32 s80, s101, 3
	s_mul_i32 s0, s0, 0x110
	s_add_i32 s0, s0, s80
	s_lshr_b32 s80, s0, 7
	s_lshl_b32 s80, s80, 2
	s_and_b32 s0, s0, 3
	s_or_b32 s0, s80, s0
	s_cmp_lt_i32 s0, 64
	s_cselect_b32 s81, 32, 0x100
	v_mov_b32_e32 v9, s81
	s_lshl_b32 s0, s0, 6
	s_add_u32 s76, s61, s0
	s_addc_u32 s77, s55, 0
	global_load_dword v1, v33, s[76:77] sc1
	s_add_i32 s84, s84, s5
	s_cmpk_gt_i32 s84, 0x87f
	s_cselect_b32 s101, s100, s84
	s_and_b32 s0, s101, 7
	s_lshr_b32 s80, s101, 3
	s_mul_i32 s0, s0, 0x110
	s_add_i32 s0, s0, s80
	s_lshr_b32 s80, s0, 7
	s_lshl_b32 s80, s80, 2
	s_and_b32 s0, s0, 3
	s_or_b32 s0, s80, s0
	s_cmp_lt_i32 s0, 64
	s_cselect_b32 s81, 32, 0x100
	v_mov_b32_e32 v10, s81
	s_lshl_b32 s0, s0, 6
	s_add_u32 s76, s61, s0
	s_addc_u32 s77, s55, 0
	global_load_dword v2, v33, s[76:77] sc1
	s_add_i32 s84, s84, s5
	s_cmpk_gt_i32 s84, 0x87f
	s_cselect_b32 s101, s100, s84
	s_and_b32 s0, s101, 7
	s_lshr_b32 s80, s101, 3
	s_mul_i32 s0, s0, 0x110
	s_add_i32 s0, s0, s80
	s_lshr_b32 s80, s0, 7
	s_lshl_b32 s80, s80, 2
	s_and_b32 s0, s0, 3
	s_or_b32 s0, s80, s0
	s_cmp_lt_i32 s0, 64
	s_cselect_b32 s81, 32, 0x100
	v_mov_b32_e32 v11, s81
	s_lshl_b32 s0, s0, 6
	s_add_u32 s76, s61, s0
	s_addc_u32 s77, s55, 0
	global_load_dword v3, v33, s[76:77] sc1
	s_add_i32 s84, s84, s5
	s_cmpk_gt_i32 s84, 0x87f
	s_cselect_b32 s101, s100, s84
	s_and_b32 s0, s101, 7
	s_lshr_b32 s80, s101, 3
	s_mul_i32 s0, s0, 0x110
	s_add_i32 s0, s0, s80
	s_lshr_b32 s80, s0, 7
	s_lshl_b32 s80, s80, 2
	s_and_b32 s0, s0, 3
	s_or_b32 s0, s80, s0
	s_cmp_lt_i32 s0, 64
	s_cselect_b32 s81, 32, 0x100
	v_mov_b32_e32 v12, s81
	s_lshl_b32 s0, s0, 6
	s_add_u32 s76, s61, s0
	s_addc_u32 s77, s55, 0
	global_load_dword v4, v33, s[76:77] sc1
	s_add_i32 s84, s84, s5
	s_cmpk_gt_i32 s84, 0x87f
	s_cselect_b32 s101, s100, s84
	s_and_b32 s0, s101, 7
	s_lshr_b32 s80, s101, 3
	s_mul_i32 s0, s0, 0x110
	s_add_i32 s0, s0, s80
	s_lshr_b32 s80, s0, 7
	s_lshl_b32 s80, s80, 2
	s_and_b32 s0, s0, 3
	s_or_b32 s0, s80, s0
	s_cmp_lt_i32 s0, 64
	s_cselect_b32 s81, 32, 0x100
	v_mov_b32_e32 v13, s81
	s_lshl_b32 s0, s0, 6
	s_add_u32 s76, s61, s0
	s_addc_u32 s77, s55, 0
	global_load_dword v5, v33, s[76:77] sc1
	s_add_i32 s84, s84, s5
	s_cmpk_gt_i32 s84, 0x87f
	s_cselect_b32 s101, s100, s84
	s_and_b32 s0, s101, 7
	s_lshr_b32 s80, s101, 3
	s_mul_i32 s0, s0, 0x110
	s_add_i32 s0, s0, s80
	s_lshr_b32 s80, s0, 7
	s_lshl_b32 s80, s80, 2
	s_and_b32 s0, s0, 3
	s_or_b32 s0, s80, s0
	s_cmp_lt_i32 s0, 64
	s_cselect_b32 s81, 32, 0x100
	v_mov_b32_e32 v14, s81
	s_lshl_b32 s0, s0, 6
	s_add_u32 s76, s61, s0
	s_addc_u32 s77, s55, 0
	global_load_dword v6, v33, s[76:77] sc1
	s_add_i32 s84, s84, s5
	s_cmpk_gt_i32 s84, 0x87f
	s_cselect_b32 s101, s100, s84
	s_and_b32 s0, s101, 7
	s_lshr_b32 s80, s101, 3
	s_mul_i32 s0, s0, 0x110
	s_add_i32 s0, s0, s80
	s_lshr_b32 s80, s0, 7
	s_lshl_b32 s80, s80, 2
	s_and_b32 s0, s0, 3
	s_or_b32 s0, s80, s0
	s_cmp_lt_i32 s0, 64
	s_cselect_b32 s81, 32, 0x100
	v_mov_b32_e32 v15, s81
	s_lshl_b32 s0, s0, 6
	s_add_u32 s76, s61, s0
	s_addc_u32 s77, s55, 0
	global_load_dword v7, v33, s[76:77] sc1
	s_waitcnt vmcnt(0)
	v_cmp_gt_u32_e32 vcc, v8, v0
	s_cbranch_vccnz .Lgp_sleepA
	v_cmp_gt_u32_e32 vcc, v9, v1
	s_cbranch_vccnz .Lgp_sleepA
	v_cmp_gt_u32_e32 vcc, v10, v2
	s_cbranch_vccnz .Lgp_sleepA
	v_cmp_gt_u32_e32 vcc, v11, v3
	s_cbranch_vccnz .Lgp_sleepA
	v_cmp_gt_u32_e32 vcc, v12, v4
	s_cbranch_vccnz .Lgp_sleepA
	v_cmp_gt_u32_e32 vcc, v13, v5
	s_cbranch_vccnz .Lgp_sleepA
	v_cmp_gt_u32_e32 vcc, v14, v6
	s_cbranch_vccnz .Lgp_sleepA
	v_cmp_gt_u32_e32 vcc, v15, v7
	s_cbranch_vccnz .Lgp_sleepA
	s_add_i32 s54, s54, 8
	s_branch .Lgp_chunkA
.Lgp_sleepA:
	s_sleep 2
	s_mov_b32 s54, 1
	s_branch .Lgp_chunkA

.LBB0_483:
	s_cmp_lg_u32 s76, 14
	s_cselect_b64 s[34:35], -1, 0
	s_or_b64 s[42:43], s[12:13], s[34:35]
	s_and_b64 vcc, exec, s[42:43]
	s_cbranch_vccnz .LBB0_482
	s_cmp_lt_i32 s71, 1
	s_mov_b64 s[42:43], -1
	s_cbranch_scc1 .LBB0_502
	s_cmp_eq_u32 s71, 1
	s_cbranch_scc0 .LBB0_501
	s_mov_b32 s54, 1
.Lgp_chunkB:
	s_mul_i32 s48, s54, s5
	s_add_i32 s48, s48, s2
	s_cmpk_gt_i32 s48, 0x7ff
	s_cbranch_scc1 .Lgp_doneB
	s_mov_b32 s100, s48
	s_mov_b32 s101, s48
	s_and_b32 s0, s101, 7
	s_lshr_b32 s46, s101, 3
	s_mul_i32 s0, s0, 0x100
	s_add_i32 s0, s0, s46
	s_lshr_b32 s46, s0, 7
	s_lshl_b32 s46, s46, 2
	s_and_b32 s0, s0, 3
	s_or_b32 s0, s46, s0
	s_cmp_lt_i32 s0, 64
	s_cselect_b32 s47, 32, 0x100
	v_mov_b32_e32 v8, s47
	s_lshl_b32 s0, s0, 6
	s_add_u32 s42, s61, s0
	s_addc_u32 s43, s55, 0
	global_load_dword v0, v33, s[42:43] sc1
	s_add_i32 s48, s48, s5
	s_cmpk_gt_i32 s48, 0x7ff
	s_cselect_b32 s101, s100, s48
	s_and_b32 s0, s101, 7
	s_lshr_b32 s46, s101, 3
	s_mul_i32 s0, s0, 0x100
	s_add_i32 s0, s0, s46
	s_lshr_b32 s46, s0, 7
	s_lshl_b32 s46, s46, 2
	s_and_b32 s0, s0, 3
	s_or_b32 s0, s46, s0
	s_cmp_lt_i32 s0, 64
	s_cselect_b32 s47, 32, 0x100
	v_mov_b32_e32 v9, s47
	s_lshl_b32 s0, s0, 6
	s_add_u32 s42, s61, s0
	s_addc_u32 s43, s55, 0
	global_load_dword v1, v33, s[42:43] sc1
	s_add_i32 s48, s48, s5
	s_cmpk_gt_i32 s48, 0x7ff
	s_cselect_b32 s101, s100, s48
	s_and_b32 s0, s101, 7
	s_lshr_b32 s46, s101, 3
	s_mul_i32 s0, s0, 0x100
	s_add_i32 s0, s0, s46
	s_lshr_b32 s46, s0, 7
	s_lshl_b32 s46, s46, 2
	s_and_b32 s0, s0, 3
	s_or_b32 s0, s46, s0
	s_cmp_lt_i32 s0, 64
	s_cselect_b32 s47, 32, 0x100
	v_mov_b32_e32 v10, s47
	s_lshl_b32 s0, s0, 6
	s_add_u32 s42, s61, s0
	s_addc_u32 s43, s55, 0
	global_load_dword v2, v33, s[42:43] sc1
	s_add_i32 s48, s48, s5
	s_cmpk_gt_i32 s48, 0x7ff
	s_cselect_b32 s101, s100, s48
	s_and_b32 s0, s101, 7
	s_lshr_b32 s46, s101, 3
	s_mul_i32 s0, s0, 0x100
	s_add_i32 s0, s0, s46
	s_lshr_b32 s46, s0, 7
	s_lshl_b32 s46, s46, 2
	s_and_b32 s0, s0, 3
	s_or_b32 s0, s46, s0
	s_cmp_lt_i32 s0, 64
	s_cselect_b32 s47, 32, 0x100
	v_mov_b32_e32 v11, s47
	s_lshl_b32 s0, s0, 6
	s_add_u32 s42, s61, s0
	s_addc_u32 s43, s55, 0
	global_load_dword v3, v33, s[42:43] sc1
	s_add_i32 s48, s48, s5
	s_cmpk_gt_i32 s48, 0x7ff
	s_cselect_b32 s101, s100, s48
	s_and_b32 s0, s101, 7
	s_lshr_b32 s46, s101, 3
	s_mul_i32 s0, s0, 0x100
	s_add_i32 s0, s0, s46
	s_lshr_b32 s46, s0, 7
	s_lshl_b32 s46, s46, 2
	s_and_b32 s0, s0, 3
	s_or_b32 s0, s46, s0
	s_cmp_lt_i32 s0, 64
	s_cselect_b32 s47, 32, 0x100
	v_mov_b32_e32 v12, s47
	s_lshl_b32 s0, s0, 6
	s_add_u32 s42, s61, s0
	s_addc_u32 s43, s55, 0
	global_load_dword v4, v33, s[42:43] sc1
	s_add_i32 s48, s48, s5
	s_cmpk_gt_i32 s48, 0x7ff
	s_cselect_b32 s101, s100, s48
	s_and_b32 s0, s101, 7
	s_lshr_b32 s46, s101, 3
	s_mul_i32 s0, s0, 0x100
	s_add_i32 s0, s0, s46
	s_lshr_b32 s46, s0, 7
	s_lshl_b32 s46, s46, 2
	s_and_b32 s0, s0, 3
	s_or_b32 s0, s46, s0
	s_cmp_lt_i32 s0, 64
	s_cselect_b32 s47, 32, 0x100
	v_mov_b32_e32 v13, s47
	s_lshl_b32 s0, s0, 6
	s_add_u32 s42, s61, s0
	s_addc_u32 s43, s55, 0
	global_load_dword v5, v33, s[42:43] sc1
	s_add_i32 s48, s48, s5
	s_cmpk_gt_i32 s48, 0x7ff
	s_cselect_b32 s101, s100, s48
	s_and_b32 s0, s101, 7
	s_lshr_b32 s46, s101, 3
	s_mul_i32 s0, s0, 0x100
	s_add_i32 s0, s0, s46
	s_lshr_b32 s46, s0, 7
	s_lshl_b32 s46, s46, 2
	s_and_b32 s0, s0, 3
	s_or_b32 s0, s46, s0
	s_cmp_lt_i32 s0, 64
	s_cselect_b32 s47, 32, 0x100
	v_mov_b32_e32 v14, s47
	s_lshl_b32 s0, s0, 6
	s_add_u32 s42, s61, s0
	s_addc_u32 s43, s55, 0
	global_load_dword v6, v33, s[42:43] sc1
	s_add_i32 s48, s48, s5
	s_cmpk_gt_i32 s48, 0x7ff
	s_cselect_b32 s101, s100, s48
	s_and_b32 s0, s101, 7
	s_lshr_b32 s46, s101, 3
	s_mul_i32 s0, s0, 0x100
	s_add_i32 s0, s0, s46
	s_lshr_b32 s46, s0, 7
	s_lshl_b32 s46, s46, 2
	s_and_b32 s0, s0, 3
	s_or_b32 s0, s46, s0
	s_cmp_lt_i32 s0, 64
	s_cselect_b32 s47, 32, 0x100
	v_mov_b32_e32 v15, s47
	s_lshl_b32 s0, s0, 6
	s_add_u32 s42, s61, s0
	s_addc_u32 s43, s55, 0
	global_load_dword v7, v33, s[42:43] sc1
	s_waitcnt vmcnt(0)
	v_cmp_gt_u32_e32 vcc, v8, v0
	s_cbranch_vccnz .Lgp_sleepB
	v_cmp_gt_u32_e32 vcc, v9, v1
	s_cbranch_vccnz .Lgp_sleepB
	v_cmp_gt_u32_e32 vcc, v10, v2
	s_cbranch_vccnz .Lgp_sleepB
	v_cmp_gt_u32_e32 vcc, v11, v3
	s_cbranch_vccnz .Lgp_sleepB
	v_cmp_gt_u32_e32 vcc, v12, v4
	s_cbranch_vccnz .Lgp_sleepB
	v_cmp_gt_u32_e32 vcc, v13, v5
	s_cbranch_vccnz .Lgp_sleepB
	v_cmp_gt_u32_e32 vcc, v14, v6
	s_cbranch_vccnz .Lgp_sleepB
	v_cmp_gt_u32_e32 vcc, v15, v7
	s_cbranch_vccnz .Lgp_sleepB
	s_add_i32 s54, s54, 8
	s_branch .Lgp_chunkB

.Lgp_doneB:
.LBB0_501:
	s_mov_b64 s[42:43], 0
